# chunkB step loop: per-wave L2 prefetch stream for the chunk two steps ahead (one dummy load per thread per step), mid-step wait removed, invariant loads hoisted
# baseline (speedup 1.0000x reference)
; __device__ __forceinline__ void chunkB_item(const Args& A, LAS unsigned char* lds, int tid, int lane, int wave, int bh) {
;     ...
;     B_LOAD(p0, q0, 0); B_LOADY(r0_, ya0, zc0, zp0, zg0, bc0, 0);
; #pragma unroll 1
;     for (int c = 0; c < 32; ++c) {
;         const int cn = c + 1 < 32 ? c + 1 : 31;
;         B_LOAD(p1, q1, cn); B_LOADY(r1_, ya1, zc1, zp1, zg1, bc1, cn);
.LBB0_278:
	s_or_b64 exec, exec, s[18:19]
	s_lshl_b64 s[18:19], s[12:13], 13
	s_add_u32 s18, s24, s18
	v_lshl_add_u64 v[16:17], v[16:17], 0, v[126:127]
	s_addc_u32 s19, s25, s19
	v_lshlrev_b32_e32 v214, 2, v96
	global_load_dwordx2 v[176:177], v[24:25], off offset:3328
	global_load_dword v172, v214, s[18:19]
	global_load_dwordx4 v[56:59], v[16:17], off
	global_load_dwordx4 v[52:55], v[16:17], off offset:64
	v_or_b32_e32 v24, s16, v106
	v_lshl_add_u64 v[16:17], v[18:19], 0, v[126:127]
	v_mov_b64_e32 v[18:19], s[94:95]
	v_mad_u64_u32 v[18:19], s[20:21], v24, s35, v[18:19]
	v_mad_i32_i24 v19, s17, v147, v19
	v_lshl_add_u64 v[18:19], v[18:19], 0, v[150:151]
	v_add_co_u32_e32 v24, vcc, s36, v18
	v_lshlrev_b32_e32 v215, 2, v106
	s_nop 0
	v_addc_co_u32_e32 v25, vcc, -1, v19, vcc
	global_load_dwordx2 v[194:195], v[16:17], off
	global_load_dwordx2 v[168:169], v[18:19], off offset:2048
	global_load_dwordx2 v[164:165], v[24:25], off offset:-1024
	global_load_dwordx2 v[166:167], v[18:19], off offset:3328
	global_load_dword v162, v215, s[18:19]
	v_readlane_b32 s20, v249, 10
	v_lshlrev_b32_e32 v16, 2, v26
	v_mov_b32_e32 v17, v95
	v_readlane_b32 s21, v249, 11
	v_readlane_b32 s22, v249, 12
	v_readlane_b32 s23, v249, 13
	v_lshl_add_u64 v[152:153], s[20:21], 0, v[16:17]
	s_lshl_b64 s[20:21], s[14:15], 22
	v_lshl_add_u64 v[154:155], s[22:23], 0, v[16:17]
	v_lshl_add_u64 v[156:157], s[6:7], 0, v[16:17]
	v_lshl_add_u64 v[16:17], s[20:21], 0, v[150:151]
	v_lshl_add_u64 v[158:159], v[116:117], 0, v[16:17]
	v_lshl_add_u64 v[160:161], v[118:119], 0, v[16:17]
	v_mov_b32_e32 v16, 0
	s_mov_b32 s39, 1
	s_lshl_b64 s[18:19], s[12:13], 5
	s_mov_b64 s[20:21], 0
	v_mov_b32_e32 v17, v16
	v_mov_b32_e32 v18, v16
	v_mov_b32_e32 v19, v16
	v_mov_b32_e32 v32, v16
	v_mov_b32_e32 v33, v16
	v_mov_b32_e32 v34, v16
	v_mov_b32_e32 v35, v16
	global_load_dwordx4 v[228:231], v[152:153], off
	global_load_dwordx4 v[250:253], v[154:155], off
	global_load_dwordx2 v[232:233], v[156:157], off
	global_load_dwordx2 v[254:255], v[156:157], off offset:8
	v_readlane_b32 s101, v249, 3
	s_lshl_b32 s98, s12, 5
	s_add_i32 s98, s98, 2
	s_cmp_lt_u32 s101, 3
	s_cbranch_scc1 .Lbpf_pq
	s_cmp_lt_u32 s101, 5
	s_cbranch_scc1 .Lbpf_ry
	s_cmp_lt_u32 s101, 7
	s_cbranch_scc1 .Lbpf_z
	s_lshl_b32 s100, s98, 8
	s_add_u32 s98, s96, 0x1cb00000
	s_addc_u32 s99, s97, 0
	s_add_u32 s98, s98, s100
	s_addc_u32 s99, s99, 0
	s_movk_i32 s100, 0x100
	s_movk_i32 s101, 0x80
	s_branch .Lbpf_done
.Lbpf_pq:
	s_mul_i32 s100, s98, 0x6000
	s_lshl_b32 s101, s101, 13
	s_add_u32 s100, s100, s101
	s_add_u32 s98, s86, s100
	s_addc_u32 s99, s87, 0
	s_movk_i32 s100, 0x6000
	s_movk_i32 s101, 0x80
	s_branch .Lbpf_done
.Lbpf_ry:
	s_lshl_b32 s100, s98, 14
	s_add_i32 s101, s101, -3
	s_lshl_b32 s101, s101, 13
	s_add_u32 s100, s100, s101
	s_add_u32 s98, s96, 0x18b00000
	s_addc_u32 s99, s97, 0
	s_add_u32 s98, s98, s100
	s_addc_u32 s99, s99, 0
	s_movk_i32 s100, 0x4000
	s_movk_i32 s101, 0x80
	s_branch .Lbpf_done
.Lbpf_z:
	s_lshr_b32 s98, s12, 3
	s_lshl_b32 s98, s98, 11
	s_add_i32 s98, s98, 0x80
	s_mul_i32 s98, s98, 0x1c00
	s_and_b32 s100, s12, 7
	s_lshl_b32 s100, s100, 7
	s_add_i32 s100, s100, 0x800
	s_cmp_eq_u32 s101, 6
	s_cselect_b32 s101, 0x500, 0
	s_add_i32 s100, s100, s101
	s_add_u32 s98, s98, s100
	s_add_u32 s98, s94, s98
	s_addc_u32 s99, s95, 0
	s_mov_b32 s100, 0x70000
	s_movk_i32 s101, 0x1c00
.Lbpf_done:
	v_mul_u32_u24_e32 v234, s101, v145
	s_waitcnt vmcnt(0)
	s_branch .LBB0_280
.LBB0_279:
	s_or_b64 exec, exec, s[22:23]
	s_waitcnt lgkmcnt(0)
	s_barrier
	ds_read2st64_b64 v[20:23], v141 offset0:36 offset1:37
	s_waitcnt lgkmcnt(1)
	ds_read2st64_b64 v[36:39], v141 offset0:38 offset1:39
	v_lshlrev_b32_e32 v42, 16, v176
	v_and_b32_e32 v43, 0xffff0000, v176
	v_lshlrev_b32_e32 v40, 16, v174
	s_waitcnt lgkmcnt(1)
	v_pk_add_f32 v[20:21], v[20:21], 0 op_sel_hi:[1,0]
	v_and_b32_e32 v41, 0xffff0000, v174
	v_pk_add_f32 v[20:21], v[20:21], v[22:23]
	v_mul_f32_e32 v23, 0xbfb8aa3b, v42
	s_waitcnt lgkmcnt(0)
	v_pk_add_f32 v[20:21], v[20:21], v[36:37]
	v_exp_f32_e32 v23, v23
	v_pk_add_f32 v[20:21], v[20:21], v[38:39]
	v_lshlrev_b32_e32 v36, 16, v170
	v_pk_mul_f32 v[20:21], v[20:21], s[10:11] op_sel_hi:[1,0]
	v_add_f32_e32 v23, 1.0, v23
	v_fma_f32 v22, -v20, v20, v21
	v_max_f32_e32 v22, 0, v22
	v_add_f32_e32 v22, 0x3a27c5ac, v22
	v_rcp_f32_e32 v38, v23
	v_mul_f32_e32 v23, 0xbfb8aa3b, v43
	v_rsq_f32_e32 v22, v22
	v_exp_f32_e32 v23, v23
	v_and_b32_e32 v37, 0xffff0000, v170
	v_pk_add_f32 v[56:57], v[198:199], v[20:21] op_sel_hi:[1,0] neg_lo:[0,1] neg_hi:[0,1]
	v_pk_add_f32 v[36:37], v[36:37], v[40:41] neg_lo:[0,1] neg_hi:[0,1]
	v_pk_mul_f32 v[56:57], v[56:57], v[22:23] op_sel_hi:[1,0]
	v_add_f32_e32 v23, 1.0, v23
	s_nop 0
	v_pk_fma_f32 v[36:37], v[36:37], v[232:233], v[40:41]
	v_lshlrev_b32_e32 v40, 16, v177
	v_rcp_f32_e32 v39, v23
	v_mul_f32_e32 v23, 0xbfb8aa3b, v40
	v_exp_f32_e32 v23, v23
	v_pk_fma_f32 v[56:57], v[228:229], v[56:57], v[250:251]
	v_and_b32_e32 v41, 0xffff0000, v177
	v_pk_fma_f32 v[36:37], v[172:173], v[36:37], v[56:57] op_sel_hi:[0,1,1]
	v_add_f32_e32 v23, 1.0, v23
	v_rcp_f32_e32 v56, v23
	v_mul_f32_e32 v23, 0xbfb8aa3b, v41
	v_exp_f32_e32 v23, v23
	v_pk_add_f32 v[20:21], v[196:197], v[20:21] op_sel_hi:[1,0] neg_lo:[0,1] neg_hi:[0,1]
	v_pk_mul_f32 v[38:39], v[38:39], v[42:43]
	v_lshlrev_b32_e32 v42, 16, v171
	v_pk_mul_f32 v[20:21], v[20:21], v[22:23] op_sel_hi:[1,0]
	v_add_f32_e32 v22, 1.0, v23
	v_rcp_f32_e32 v57, v22
	v_pk_mul_f32 v[36:37], v[38:39], v[36:37]
	v_lshlrev_b32_e32 v38, 16, v175
	v_and_b32_e32 v39, 0xffff0000, v175
	v_and_b32_e32 v43, 0xffff0000, v171
	v_pk_add_f32 v[22:23], v[42:43], v[38:39] neg_lo:[0,1] neg_hi:[0,1]
	v_pk_fma_f32 v[20:21], v[230:231], v[20:21], v[252:253]
	v_pk_fma_f32 v[22:23], v[22:23], v[254:255], v[38:39]
	v_lshl_add_u64 v[42:43], v[160:161], 0, s[20:21]
	v_pk_fma_f32 v[20:21], v[172:173], v[22:23], v[20:21] op_sel_hi:[0,1,1]
	v_pk_mul_f32 v[22:23], v[56:57], v[40:41]
	v_cvt_pk_bf16_f32 v40, v36, v37
	v_pk_mul_f32 v[38:39], v[22:23], v[20:21]
	ds_read2st64_b64 v[20:23], v143 offset0:36 offset1:37
	v_cvt_pk_bf16_f32 v41, v38, v39
	ds_read2st64_b64 v[36:39], v143 offset0:38 offset1:39
	global_store_dwordx2 v[42:43], v[40:41], off
	v_lshlrev_b32_e32 v40, 16, v164
	s_waitcnt lgkmcnt(1)
; __device__ __forceinline__ void chunkB_item(const Args& A, LAS unsigned char* lds, int tid, int lane, int wave, int bh) {
;     ...
;         for (int nn = 0; nn < 2; ++nn) { p0[nn][0] = p1[nn][0]; p0[nn][1] = p1[nn][1]; q0[nn] = q1[nn]; r0_[nn][0] = r1_[nn][0]; r0_[nn][1] = r1_[nn][1];
;             ya0[nn] = ya1[nn]; zc0[nn] = zc1[nn]; zp0[nn] = zp1[nn]; zg0[nn] = zg1[nn]; bc0[nn] = bc1[nn]; }
	v_pk_add_f32 v[20:21], v[20:21], 0 op_sel_hi:[1,0]
	v_and_b32_e32 v41, 0xffff0000, v164
	v_pk_add_f32 v[20:21], v[20:21], v[22:23]
	s_waitcnt lgkmcnt(0)
	v_pk_add_f32 v[20:21], v[20:21], v[36:37]
	v_lshlrev_b32_e32 v36, 16, v168
	v_pk_add_f32 v[20:21], v[20:21], v[38:39]
	v_lshlrev_b32_e32 v38, 16, v166
	v_mul_f32_e32 v23, 0xbfb8aa3b, v38
	v_exp_f32_e32 v23, v23
	v_pk_mul_f32 v[20:21], v[20:21], s[10:11] op_sel_hi:[1,0]
	v_and_b32_e32 v39, 0xffff0000, v166
	v_fma_f32 v22, -v20, v20, v21
	v_max_f32_e32 v22, 0, v22
	v_add_f32_e32 v23, 1.0, v23
	v_add_f32_e32 v22, 0x3a27c5ac, v22
	v_rcp_f32_e32 v42, v23
	v_mul_f32_e32 v23, 0xbfb8aa3b, v39
	v_rsq_f32_e32 v22, v22
	v_exp_f32_e32 v23, v23
	v_and_b32_e32 v37, 0xffff0000, v168
	v_pk_add_f32 v[54:55], v[54:55], v[20:21] op_sel_hi:[1,0] neg_lo:[0,1] neg_hi:[0,1]
	v_pk_add_f32 v[40:41], v[40:41], v[36:37] neg_lo:[0,1] neg_hi:[0,1]
	v_pk_mul_f32 v[54:55], v[54:55], v[22:23] op_sel_hi:[1,0]
	v_add_f32_e32 v23, 1.0, v23
	v_pk_fma_f32 v[36:37], v[40:41], v[232:233], v[36:37]
	v_lshlrev_b32_e32 v40, 16, v167
	v_rcp_f32_e32 v43, v23
	v_mul_f32_e32 v23, 0xbfb8aa3b, v40
	v_exp_f32_e32 v23, v23
	v_pk_fma_f32 v[54:55], v[228:229], v[54:55], v[250:251]
	v_and_b32_e32 v41, 0xffff0000, v167
	v_pk_fma_f32 v[36:37], v[162:163], v[36:37], v[54:55] op_sel_hi:[0,1,1]
	v_add_f32_e32 v23, 1.0, v23
	v_rcp_f32_e32 v54, v23
	v_mul_f32_e32 v23, 0xbfb8aa3b, v41
	v_exp_f32_e32 v23, v23
	v_pk_add_f32 v[20:21], v[52:53], v[20:21] op_sel_hi:[1,0] neg_lo:[0,1] neg_hi:[0,1]
	v_pk_mul_f32 v[38:39], v[42:43], v[38:39]
	v_lshlrev_b32_e32 v42, 16, v165
	v_pk_mul_f32 v[20:21], v[20:21], v[22:23] op_sel_hi:[1,0]
	v_add_f32_e32 v22, 1.0, v23
	v_rcp_f32_e32 v55, v22
	v_pk_mul_f32 v[36:37], v[38:39], v[36:37]
	v_lshlrev_b32_e32 v38, 16, v169
	v_and_b32_e32 v39, 0xffff0000, v169
	v_and_b32_e32 v43, 0xffff0000, v165
	v_pk_add_f32 v[22:23], v[42:43], v[38:39] neg_lo:[0,1] neg_hi:[0,1]
	v_pk_fma_f32 v[20:21], v[230:231], v[20:21], v[252:253]
	v_pk_fma_f32 v[22:23], v[22:23], v[254:255], v[38:39]
	v_pk_fma_f32 v[20:21], v[162:163], v[22:23], v[20:21] op_sel_hi:[0,1,1]
	v_pk_mul_f32 v[22:23], v[54:55], v[40:41]
	v_pk_mul_f32 v[20:21], v[22:23], v[20:21]
	v_cvt_pk_bf16_f32 v22, v36, v37
	v_cvt_pk_bf16_f32 v23, v20, v21
	v_lshl_add_u64 v[20:21], v[158:159], 0, s[20:21]
	s_add_u32 s20, s20, 0x20000
	global_store_dwordx2 v[20:21], v[22:23], off
	s_addc_u32 s21, s21, 0
	s_add_i32 s39, s39, 1
	s_waitcnt vmcnt(3)
	v_mov_b64_e32 v[58:59], v[46:47]
	v_mov_b64_e32 v[164:165], v[192:193]
	v_mov_b64_e32 v[54:55], v[50:51]
	v_mov_b64_e32 v[38:39], v[26:27]
	v_mov_b64_e32 v[20:21], v[28:29]
	s_cmp_eq_u32 s20, 0x400000
	v_mov_b64_e32 v[170:171], v[186:187]
	v_mov_b64_e32 v[166:167], v[190:191]
	v_mov_b64_e32 v[176:177], v[184:185]
	v_mov_b64_e32 v[174:175], v[182:183]
	v_mov_b64_e32 v[168:169], v[188:189]
	v_mov_b32_e32 v162, v127
	v_mov_b32_e32 v172, v125
	v_mov_b64_e32 v[56:57], v[44:45]
	v_mov_b64_e32 v[52:53], v[48:49]
	v_mov_b64_e32 v[36:37], v[24:25]
	v_mov_b64_e32 v[22:23], v[30:31]
	v_mov_b32_e32 v40, v216
	v_mov_b32_e32 v41, v217
	v_mov_b32_e32 v42, v218
	v_mov_b32_e32 v43, v219
	v_mov_b32_e32 v196, v178
	v_mov_b32_e32 v197, v179
	v_mov_b32_e32 v194, v180
	v_mov_b32_e32 v195, v181
	s_cbranch_scc1 .LBB0_268
.LBB0_280:
	s_cmp_lg_u32 s20, 0x3e0000
	s_cselect_b32 s15, s39, 31
	s_add_u32 s22, s18, s15
	s_addc_u32 s23, s19, 0
	s_mul_i32 s40, s23, 0x6000
	s_mul_hi_u32 s41, s22, 0x6000
	s_add_i32 s41, s41, s40
	s_mul_i32 s40, s22, 0x6000
	s_add_u32 s40, s86, s40
	s_addc_u32 s41, s87, s41
	s_waitcnt vmcnt(12)
	v_mov_b64_e32 v[226:227], v[10:11]
	s_add_u32 s42, s40, 0x2000
	v_mov_b64_e32 v[224:225], v[8:9]
	s_addc_u32 s43, s41, 0
	v_lshl_add_u64 v[8:9], s[40:41], 0, v[94:95]
	s_lshl_b64 s[40:41], s[22:23], 14
	s_add_u32 s40, s3, s40
	s_addc_u32 s41, s11, s41
	s_lshl_b64 s[22:23], s[22:23], 8
	s_add_u32 s22, s24, s22
	v_mov_b64_e32 v[74:75], v[6:7]
	v_mov_b32_e32 v125, v95
	v_mov_b32_e32 v127, v95
	s_addc_u32 s23, s25, s23
	s_lshl_b32 s15, s15, 6
	v_mov_b64_e32 v[72:73], v[4:5]
	v_mov_b64_e32 v[200:201], v[2:3]
	s_waitcnt vmcnt(11)
; __device__ __forceinline__ void chunkB_item(const Args& A, LAS unsigned char* lds, int tid, int lane, int wave, int bh) {
;     ...
;         B_LOAD(p1, q1, cn); B_LOADY(r1_, ya1, zc1, zp1, zg1, bc1, cn);
	v_mov_b64_e32 v[222:223], v[14:15]
	v_lshl_add_u64 v[4:5], v[8:9], 0, v[124:125]
	v_lshl_add_u64 v[10:11], v[98:99], 2, s[42:43]
	v_lshl_add_u64 v[24:25], v[104:105], 2, s[42:43]
	v_lshl_add_u64 v[8:9], v[8:9], 0, v[126:127]
	s_add_u32 s15, s16, s15
	v_mov_b64_e32 v[198:199], v[0:1]
	v_mov_b64_e32 v[220:221], v[12:13]
	v_mov_b32_e32 v76, v210
	v_mov_b32_e32 v77, v211
	v_mov_b32_e32 v78, v212
	v_mov_b32_e32 v79, v213
	global_load_dwordx4 v[0:3], v[4:5], off
	s_nop 0
	global_load_dwordx4 v[4:7], v[4:5], off offset:64
	v_lshl_add_u64 v[12:13], v[100:101], 2, s[42:43]
	v_lshl_add_u64 v[14:15], v[102:103], 2, s[42:43]
	global_load_dword v210, v[10:11], off
	global_load_dword v211, v[12:13], off
	global_load_dword v212, v[14:15], off
	global_load_dword v213, v[24:25], off
	s_nop 0
	global_load_dwordx4 v[24:27], v[8:9], off
	global_load_dwordx4 v[28:31], v[8:9], off offset:64
	v_lshl_add_u64 v[8:9], v[108:109], 2, s[42:43]
	v_mov_b32_e32 v149, v95
	v_or_b32_e32 v48, s15, v96
	v_mov_b64_e32 v[62:63], s[94:95]
	v_lshl_add_u64 v[10:11], v[110:111], 2, s[42:43]
	v_lshl_add_u64 v[12:13], v[112:113], 2, s[42:43]
	v_lshl_add_u64 v[14:15], v[114:115], 2, s[42:43]
	global_load_dword v216, v[8:9], off
	global_load_dword v217, v[10:11], off
	global_load_dword v218, v[12:13], off
	global_load_dword v219, v[14:15], off
	s_addc_u32 s42, s17, 0
	v_lshl_add_u64 v[44:45], s[40:41], 0, v[94:95]
	v_lshl_add_u64 v[8:9], s[40:41], 0, v[148:149]
	v_mad_u64_u32 v[48:49], s[40:41], v48, s35, v[62:63]
	v_mad_i32_i24 v49, s42, v147, v49
	v_mov_b32_e32 v151, v95
	v_or_b32_e32 v64, s15, v106
	v_lshl_add_u64 v[48:49], v[48:49], 0, v[150:151]
	v_mad_u64_u32 v[62:63], s[40:41], v64, s35, v[62:63]
	v_add_co_u32_e32 v50, vcc, s36, v48
	v_mad_i32_i24 v63, s42, v147, v63
	v_lshl_add_u64 v[60:61], v[8:9], 0, s[8:9]
	v_addc_co_u32_e32 v51, vcc, -1, v49, vcc
	v_lshl_add_u64 v[62:63], v[62:63], 0, v[150:151]
	v_lshl_add_u64 v[12:13], v[44:45], 0, v[124:125]
	v_lshl_add_u64 v[46:47], v[60:61], 0, v[124:125]
	v_add_co_u32_e32 v64, vcc, s36, v62
	global_load_dwordx4 v[8:11], v[12:13], off
	s_nop 0
	global_load_dwordx4 v[12:15], v[12:13], off offset:64
	s_nop 0
	global_load_dwordx2 v[178:179], v[46:47], off
	global_load_dwordx2 v[182:183], v[48:49], off offset:2048
	global_load_dwordx2 v[186:187], v[50:51], off offset:-1024
	global_load_dwordx2 v[184:185], v[48:49], off offset:3328
	v_lshl_add_u64 v[48:49], v[44:45], 0, v[126:127]
	v_lshl_add_u64 v[60:61], v[60:61], 0, v[126:127]
	v_addc_co_u32_e32 v65, vcc, -1, v63, vcc
	global_load_dwordx4 v[44:47], v[48:49], off
	s_nop 0
	global_load_dwordx4 v[48:51], v[48:49], off offset:64
	s_nop 0
	global_load_dwordx2 v[180:181], v[60:61], off
	global_load_dwordx2 v[188:189], v[62:63], off offset:2048
	global_load_dwordx2 v[192:193], v[64:65], off offset:-1024
	global_load_dwordx2 v[190:191], v[62:63], off offset:3328
	global_load_dword v125, v214, s[22:23]
	global_load_dword v127, v215, s[22:23]
	global_load_dword v235, v234, s[98:99]
	s_add_u32 s98, s98, s100
	s_addc_u32 s99, s99, 0
	s_nop 0
	v_cvt_pk_bf16_f32 v80, v16, 0
	v_lshlrev_b32_e32 v81, 16, v80
	v_sub_f32_e32 v16, v16, v81
	v_cvt_pk_bf16_f32 v16, v16, s0
	ds_write_b16 v107, v80
	ds_write_b16 v107, v16 offset:9216
	v_cvt_pk_bf16_f32 v16, v17, 0
	v_lshlrev_b32_e32 v80, 16, v16
	v_sub_f32_e32 v17, v17, v80
	v_cvt_pk_bf16_f32 v17, v17, s0
	ds_write_b16 v107, v16 offset:144
	ds_write_b16 v107, v17 offset:9360
	v_cvt_pk_bf16_f32 v16, v18, 0
	v_lshlrev_b32_e32 v17, 16, v16
	v_sub_f32_e32 v17, v18, v17
	v_cvt_pk_bf16_f32 v17, v17, s0
	ds_write_b16 v107, v16 offset:288
	ds_write_b16 v107, v17 offset:9504
	v_cvt_pk_bf16_f32 v16, v19, 0
	v_lshlrev_b32_e32 v17, 16, v16
	v_sub_f32_e32 v17, v19, v17
	v_cvt_pk_bf16_f32 v17, v17, s0
	ds_write_b16 v107, v16 offset:432
	ds_write_b16 v107, v17 offset:9648
	v_cvt_pk_bf16_f32 v16, v32, 0
	v_lshlrev_b32_e32 v17, 16, v16
	v_sub_f32_e32 v17, v32, v17
	v_cvt_pk_bf16_f32 v17, v17, s0
	ds_write_b16 v135, v16
	ds_write_b16 v135, v17 offset:9216
	v_cvt_pk_bf16_f32 v16, v33, 0
	v_lshlrev_b32_e32 v17, 16, v16
	v_sub_f32_e32 v17, v33, v17
	v_cvt_pk_bf16_f32 v17, v17, s0
	ds_write_b16 v135, v16 offset:144
	ds_write_b16 v135, v17 offset:9360
	v_cvt_pk_bf16_f32 v16, v34, 0
	v_lshlrev_b32_e32 v17, 16, v16
	v_sub_f32_e32 v17, v34, v17
	v_cvt_pk_bf16_f32 v17, v17, s0
	ds_write_b16 v135, v16 offset:288
	ds_write_b16 v135, v17 offset:9504
	v_cvt_pk_bf16_f32 v16, v35, 0
	v_lshlrev_b32_e32 v17, 16, v16
	v_sub_f32_e32 v17, v35, v17
	v_cvt_pk_bf16_f32 v17, v17, s0
	ds_write_b16 v135, v16 offset:432
	ds_write_b16 v135, v17 offset:9648
	s_waitcnt lgkmcnt(0)
	s_barrier
	ds_read_b128 v[80:83], v139
	ds_read_b128 v[32:35], v139 offset:64
	s_waitcnt lgkmcnt(1)
	v_mfma_f32_16x16x32_bf16 v[16:19], v[80:83], v[198:201], v[76:79]
	ds_read_b128 v[84:87], v139 offset:9216
	s_nop 1
	ds_read_b128 v[76:79], v139 offset:9280
	s_waitcnt vmcnt(39)
	v_lshlrev_b32_e32 v202, 16, v196
	v_and_b32_e32 v203, 0xffff0000, v196
	s_waitcnt lgkmcnt(1)
	v_mfma_f32_16x16x32_bf16 v[16:19], v[84:87], v[198:201], v[16:19]
	v_lshlrev_b32_e32 v196, 16, v197
	v_and_b32_e32 v197, 0xffff0000, v197
	v_and_b32_e32 v151, 64, v209
	v_mfma_f32_16x16x32_bf16 v[198:201], v[80:83], v[224:227], 0
	v_xor_b32_e32 v149, 16, v209
	v_add_u32_e32 v151, 64, v151
	v_cmp_lt_i32_e32 vcc, v149, v151
	v_mfma_f32_16x16x32_bf16 v[198:201], v[32:35], v[220:223], v[198:201]
	v_xor_b32_e32 v224, 32, v209
	v_cndmask_b32_e32 v149, v209, v149, vcc
	v_lshlrev_b32_e32 v149, 2, v149
	v_cmp_lt_i32_e32 vcc, v224, v151
	v_mfma_f32_16x16x32_bf16 v[16:19], v[32:35], v[72:75], v[16:19]
	s_nop 2
	v_add_f32_e64 v198, v198, v202
	v_add_f32_e64 v199, v199, v203
	v_pk_add_f32 v[196:197], v[200:201], v[196:197]
	v_pk_mul_f32 v[200:201], v[198:199], v[198:199]
	v_pk_mul_f32 v[202:203], v[196:197], v[196:197]
	v_mov_b32_e32 v220, v198
	v_mov_b32_e32 v221, v200
	v_mov_b32_e32 v200, v199
	v_pk_add_f32 v[200:201], v[220:221], v[200:201]
	v_mov_b32_e32 v220, v196
	v_mov_b32_e32 v221, v202
	v_mov_b32_e32 v202, v197
	v_pk_add_f32 v[202:203], v[220:221], v[202:203]
	v_cndmask_b32_e32 v151, v209, v224, vcc
	v_pk_add_f32 v[200:201], v[200:201], v[202:203]
	ds_bpermute_b32 v202, v149, v200
	ds_bpermute_b32 v203, v149, v201
	v_lshlrev_b32_e32 v151, 2, v151
	s_waitcnt lgkmcnt(2)
	v_mfma_f32_16x16x32_bf16 v[16:19], v[76:79], v[72:75], v[16:19]
	s_waitcnt lgkmcnt(0)
	v_pk_add_f32 v[200:201], v[200:201], v[202:203]
	ds_bpermute_b32 v202, v151, v200
	ds_bpermute_b32 v203, v151, v201
	s_and_saveexec_b64 s[22:23], s[30:31]
	s_cbranch_execz .LBB0_282
	s_waitcnt lgkmcnt(0)
	v_pk_add_f32 v[72:73], v[200:201], v[202:203]
	v_add_u32_e32 v74, s26, v130
	ds_write_b64 v74, v[72:73] offset:18432
